# HGRN f32 scan-output dword stores: sc1 nt (write-through streaming), on the sc1 nt GEMM-store version
# speedup vs baseline: 1.0059x; 1.0059x over previous
; DI float bflo(unsigned w) { return __uint_as_float(w << 16); }
; DI float bfhi(unsigned w) { return __uint_as_float(w & 0xffff0000u); }
; DI float hflo(unsigned w) { return (float)__builtin_bit_cast(_Float16, (u16)(w & 0xffffu)); }
; DI float hfhi(unsigned w) { return (float)__builtin_bit_cast(_Float16, (u16)(w >> 16)); }
; DI void hgrn_unit(const P& p, int l, int unit, char* lds_all) {
;     ...
;   for (int c = 0; c < 36; ++c) {
;     int base;
;     if (c < 4) base = 2048 + (dir ? (3 - c) : c) * 64;
;     else base = (dir ? (31 - (c - 4)) : (c - 4)) * 64;
;     const int tok = base + (dir ? 63 - tau : tau);
;     float qv[16], kk[16];
;     {
;       const uint4* qp = (const uint4*)(qs + (size_t)tok * 64 + kc);
;       const uint4* zp = (const uint4*)(zs + (size_t)tok * 64 + kc);
;       const uint4* vp = (const uint4*)(is + (size_t)tok * 64 + kc);
;       const uint4 q0 = qp[0], q1 = qp[1], z0 = zp[0], z1 = zp[1], v0 = vp[0], v1 = vp[1];
;       const unsigned qw[8] = {q0.x, q0.y, q0.z, q0.w, q1.x, q1.y, q1.z, q1.w};
;       const unsigned zw[8] = {z0.x, z0.y, z0.z, z0.w, z1.x, z1.y, z1.z, z1.w};
;       const unsigned vw[8] = {v0.x, v0.y, v0.z, v0.w, v1.x, v1.y, v1.z, v1.w};
; #pragma unroll
;       for (int e = 0; e < 8; ++e) {
;         qv[2 * e] = bflo(qw[e]);
;         qv[2 * e + 1] = bfhi(qw[e]);
;         const float za = hflo(zw[e]), zb = hfhi(zw[e]);
;         const float fa = lbv[2 * e] + (1.f - lbv[2 * e]) / (1.f + __expf(-za));
;         const float fb = lbv[2 * e + 1] + (1.f - lbv[2 * e + 1]) / (1.f + __expf(-zb));
;         kk[2 * e] = 1.f - fa;
;         kk[2 * e + 1] = 1.f - fb;
;         Lf[tau * 65 + kc + 2 * e] = __logf(fa);
;         Lf[tau * 65 + kc + 2 * e + 1] = __logf(fb);
;         Vt[(kc + 2 * e) * 72 + tau] = (u16)(vw[e] & 0xffffu);
;         Vt[(kc + 2 * e + 1) * 72 + tau] = (u16)(vw[e] >> 16);
;       }
.LBB0_933:
	v_add_u32_e32 v2, v127, v99
	v_ashrrev_i32_e32 v3, 31, v2
	v_lshlrev_b64 v[2:3], 7, v[2:3]
	v_lshl_add_u64 v[4:5], v[44:45], 0, v[2:3]
	v_lshl_add_u64 v[6:7], v[46:47], 0, v[2:3]
	v_lshl_add_u64 v[12:13], v[48:49], 0, v[2:3]
	global_load_dwordx4 v[94:97], v[4:5], off offset:16
	global_load_dwordx4 v[8:11], v[4:5], off
	global_load_dwordx4 v[128:131], v[6:7], off offset:16
	global_load_dwordx4 v[14:17], v[6:7], off
	s_nop 0
	global_load_dwordx4 v[2:5], v[12:13], off offset:16
	global_load_dwordx4 v[18:21], v[12:13], off
	s_add_i32 s26, s26, -1
	s_add_i32 s24, s24, 1
	s_cmp_eq_u32 s26, -1
	s_waitcnt vmcnt(0)
	ds_write_b16 v103, v18 offset:45312
	ds_write_b16_d16_hi v104, v18 offset:45456
	v_lshlrev_b32_e32 v6, 16, v8
	v_and_b32_e32 v7, 0xffff0000, v8
	v_cvt_f32_f16_e32 v8, v14
	v_cvt_f32_f16_sdwa v12, v14 dst_sel:DWORD dst_unused:UNUSED_PAD src0_sel:WORD_1
	v_and_b32_e32 v13, 0xffff0000, v9
	ds_write_b16 v104, v19 offset:45600
	ds_write_b16_d16_hi v105, v19 offset:45456
	v_mul_f32_e32 v8, 0xbfb8aa3b, v8
	v_exp_f32_e32 v92, v8
	v_mul_f32_e32 v8, 0xbfb8aa3b, v12
	v_exp_f32_e32 v93, v8
	v_cvt_f32_f16_e32 v8, v15
	v_lshlrev_b32_e32 v12, 16, v9
	v_cvt_f32_f16_sdwa v9, v15 dst_sel:DWORD dst_unused:UNUSED_PAD src0_sel:WORD_1
	ds_write_b16 v105, v20 offset:45600
	ds_write_b16_d16_hi v106, v20 offset:45456
	v_mul_f32_e32 v8, 0xbfb8aa3b, v8
	v_exp_f32_e32 v14, v8
	v_mul_f32_e32 v8, 0xbfb8aa3b, v9
	v_exp_f32_e32 v15, v8
	v_cvt_f32_f16_e32 v8, v16
	v_cvt_f32_f16_sdwa v9, v16 dst_sel:DWORD dst_unused:UNUSED_PAD src0_sel:WORD_1
	ds_write_b16 v106, v21 offset:45600
	ds_write_b16_d16_hi v107, v21 offset:45456
	ds_write_b16 v107, v2 offset:45600
	ds_write_b16_d16_hi v108, v2 offset:45456
	v_mul_f32_e32 v8, 0xbfb8aa3b, v8
	v_exp_f32_e32 v90, v8
	v_mul_f32_e32 v8, 0xbfb8aa3b, v9
	v_exp_f32_e32 v91, v8
	v_cvt_f32_f16_e32 v8, v17
	v_cvt_f32_f16_sdwa v9, v17 dst_sel:DWORD dst_unused:UNUSED_PAD src0_sel:WORD_1
	v_cvt_f32_f16_e32 v2, v129
	ds_write_b16 v108, v3 offset:45600
	ds_write_b16_d16_hi v109, v3 offset:45456
	v_mul_f32_e32 v8, 0xbfb8aa3b, v8
	v_exp_f32_e32 v88, v8
	v_mul_f32_e32 v8, 0xbfb8aa3b, v9
	v_exp_f32_e32 v89, v8
	v_cvt_f32_f16_e32 v8, v128
	v_cvt_f32_f16_sdwa v9, v128 dst_sel:DWORD dst_unused:UNUSED_PAD src0_sel:WORD_1
	v_mul_f32_e32 v2, 0xbfb8aa3b, v2
	v_exp_f32_e32 v16, v2
	v_mul_f32_e32 v8, 0xbfb8aa3b, v8
	v_exp_f32_e32 v18, v8
	v_mul_f32_e32 v8, 0xbfb8aa3b, v9
	v_exp_f32_e32 v19, v8
	v_cvt_f32_f16_sdwa v8, v129 dst_sel:DWORD dst_unused:UNUSED_PAD src0_sel:WORD_1
	v_cvt_f32_f16_sdwa v3, v130 dst_sel:DWORD dst_unused:UNUSED_PAD src0_sel:WORD_1
	v_lshlrev_b32_e32 v26, 16, v10
	v_and_b32_e32 v27, 0xffff0000, v10
	v_mul_f32_e32 v2, 0xbfb8aa3b, v8
	v_exp_f32_e32 v17, v2
	v_cvt_f32_f16_e32 v2, v130
	v_lshlrev_b32_e32 v24, 16, v11
	v_and_b32_e32 v25, 0xffff0000, v11
	ds_write_b16 v109, v4 offset:45600
	ds_write_b16_d16_hi v110, v4 offset:45456
	v_mul_f32_e32 v2, 0xbfb8aa3b, v2
	v_exp_f32_e32 v10, v2
	v_mul_f32_e32 v2, 0xbfb8aa3b, v3
	v_exp_f32_e32 v11, v2
	v_cvt_f32_f16_e32 v2, v131
	v_cvt_f32_f16_sdwa v3, v131 dst_sel:DWORD dst_unused:UNUSED_PAD src0_sel:WORD_1
	ds_write_b16 v110, v5 offset:45600
	ds_write_b16_d16_hi v111, v5 offset:45456
	v_lshlrev_b32_e32 v22, 16, v94
	v_mul_f32_e32 v2, 0xbfb8aa3b, v2
	v_exp_f32_e32 v8, v2
	v_mul_f32_e32 v2, 0xbfb8aa3b, v3
	v_exp_f32_e32 v9, v2
	v_pk_add_f32 v[2:3], v[92:93], 1.0 op_sel_hi:[1,0]
	v_and_b32_e32 v23, 0xffff0000, v94
	v_div_scale_f32 v4, s[82:83], v3, v3, v53
	v_rcp_f32_e32 v5, v4
	v_pk_add_f32 v[88:89], v[88:89], 1.0 op_sel_hi:[1,0]
	v_pk_add_f32 v[18:19], v[18:19], 1.0 op_sel_hi:[1,0]
	v_lshlrev_b32_e32 v20, 16, v95
	v_fma_f32 v92, -v4, v5, 1.0
	v_fmac_f32_e32 v5, v92, v5
	v_div_scale_f32 v92, vcc, v53, v3, v53
	v_mul_f32_e32 v93, v92, v5
	v_fma_f32 v94, -v4, v93, v92
	v_fmac_f32_e32 v93, v94, v5
	v_fma_f32 v4, -v4, v93, v92
	v_div_fmas_f32 v4, v4, v5, v93
	v_div_fixup_f32 v3, v4, v3, v53
	v_div_scale_f32 v4, s[82:83], v2, v2, v52
	v_rcp_f32_e32 v5, v4
	v_and_b32_e32 v21, 0xffff0000, v95
	v_pk_add_f32 v[16:17], v[16:17], 1.0 op_sel_hi:[1,0]
	v_lshlrev_b32_e32 v86, 16, v96
	v_fma_f32 v92, -v4, v5, 1.0
	v_fmac_f32_e32 v5, v92, v5
	v_div_scale_f32 v92, vcc, v52, v2, v52
	v_mul_f32_e32 v93, v92, v5
	v_fma_f32 v94, -v4, v93, v92
	v_fmac_f32_e32 v93, v94, v5
	v_fma_f32 v4, -v4, v93, v92
	v_div_fmas_f32 v4, v4, v5, v93
	v_div_fixup_f32 v2, v4, v2, v52
	v_pk_add_f32 v[4:5], v[28:29], v[2:3]
	v_and_b32_e32 v87, 0xffff0000, v96
	v_cmp_gt_f32_e32 vcc, s37, v4
	v_pk_add_f32 v[2:3], v[4:5], 1.0 op_sel_hi:[1,0] neg_lo:[1,0] neg_hi:[1,0]
	v_lshlrev_b32_e32 v84, 16, v97
	v_cndmask_b32_e64 v92, 0, 32, vcc
	v_ldexp_f32 v4, v4, v92
	v_log_f32_e32 v4, v4
	v_and_b32_e32 v85, 0xffff0000, v97
	v_pk_add_f32 v[10:11], v[10:11], 1.0 op_sel_hi:[1,0]
	v_pk_add_f32 v[8:9], v[8:9], 1.0 op_sel_hi:[1,0]
	v_mul_f32_e32 v92, 0x3f317217, v4
	v_fma_f32 v92, v4, s22, -v92
	v_fmac_f32_e32 v92, 0x3377d1cf, v4
	v_fmac_f32_e32 v92, 0x3f317217, v4
	v_cmp_lt_f32_e64 s[82:83], |v4|, s31
	s_nop 1
	v_cndmask_b32_e64 v4, v4, v92, s[82:83]
	v_cndmask_b32_e32 v92, 0, v225, vcc
	v_cmp_gt_f32_e32 vcc, s37, v5
	v_sub_f32_e32 v4, v4, v92
	s_nop 0
	v_cndmask_b32_e64 v92, 0, 32, vcc
	v_ldexp_f32 v5, v5, v92
	v_log_f32_e32 v5, v5
	s_nop 0
	v_mul_f32_e32 v92, 0x3f317217, v5
	v_fma_f32 v92, v5, s22, -v92
	v_fmac_f32_e32 v92, 0x3377d1cf, v5
	v_fmac_f32_e32 v92, 0x3f317217, v5
	v_cmp_lt_f32_e64 s[82:83], |v5|, s31
	s_nop 1
	v_cndmask_b32_e64 v5, v5, v92, s[82:83]
	v_cndmask_b32_e32 v92, 0, v225, vcc
	v_sub_f32_e32 v5, v5, v92
	ds_write2_b32 v100, v4, v5 offset1:1
	v_pk_add_f32 v[4:5], v[14:15], 1.0 op_sel_hi:[1,0]
	s_nop 0
; DI float bflo(unsigned w) { return __uint_as_float(w << 16); }
; DI float bfhi(unsigned w) { return __uint_as_float(w & 0xffff0000u); }
; DI float hflo(unsigned w) { return (float)__builtin_bit_cast(_Float16, (u16)(w & 0xffffu)); }
; DI float hfhi(unsigned w) { return (float)__builtin_bit_cast(_Float16, (u16)(w >> 16)); }
; DI void hgrn_unit(const P& p, int l, int unit, char* lds_all) {
;     ...
;       for (int e = 0; e < 8; ++e) {
;         qv[2 * e] = bflo(qw[e]);
;         qv[2 * e + 1] = bfhi(qw[e]);
;         const float za = hflo(zw[e]), zb = hfhi(zw[e]);
;         const float fa = lbv[2 * e] + (1.f - lbv[2 * e]) / (1.f + __expf(-za));
;         const float fb = lbv[2 * e + 1] + (1.f - lbv[2 * e + 1]) / (1.f + __expf(-zb));
;         kk[2 * e] = 1.f - fa;
;         kk[2 * e + 1] = 1.f - fb;
;         Lf[tau * 65 + kc + 2 * e] = __logf(fa);
;         Lf[tau * 65 + kc + 2 * e + 1] = __logf(fb);
;         Vt[(kc + 2 * e) * 72 + tau] = (u16)(vw[e] & 0xffffu);
;         Vt[(kc + 2 * e + 1) * 72 + tau] = (u16)(vw[e] >> 16);
;       }
	v_div_scale_f32 v14, s[82:83], v5, v5, v55
	v_rcp_f32_e32 v15, v14
	s_nop 0
	v_fma_f32 v92, -v14, v15, 1.0
	v_fmac_f32_e32 v15, v92, v15
	v_div_scale_f32 v92, vcc, v55, v5, v55
	v_mul_f32_e32 v93, v92, v15
	v_fma_f32 v94, -v14, v93, v92
	v_fmac_f32_e32 v93, v94, v15
	v_fma_f32 v14, -v14, v93, v92
	v_div_fmas_f32 v14, v14, v15, v93
	v_div_fixup_f32 v5, v14, v5, v55
	v_div_scale_f32 v14, s[82:83], v4, v4, v54
	v_rcp_f32_e32 v15, v14
	s_nop 0
	v_fma_f32 v92, -v14, v15, 1.0
	v_fmac_f32_e32 v15, v92, v15
	v_div_scale_f32 v92, vcc, v54, v4, v54
	v_mul_f32_e32 v93, v92, v15
	v_fma_f32 v94, -v14, v93, v92
	v_fmac_f32_e32 v93, v94, v15
	v_fma_f32 v14, -v14, v93, v92
	v_div_fmas_f32 v14, v14, v15, v93
	v_div_fixup_f32 v4, v14, v4, v54
	v_pk_add_f32 v[4:5], v[30:31], v[4:5]
	s_nop 0
	v_cmp_gt_f32_e32 vcc, s37, v4
	v_pk_add_f32 v[14:15], v[4:5], 1.0 op_sel_hi:[1,0] neg_lo:[1,0] neg_hi:[1,0]
	s_nop 0
	v_cndmask_b32_e64 v92, 0, 32, vcc
	v_ldexp_f32 v4, v4, v92
	v_log_f32_e32 v4, v4
	s_nop 0
	v_mul_f32_e32 v92, 0x3f317217, v4
	v_fma_f32 v92, v4, s22, -v92
	v_fmac_f32_e32 v92, 0x3377d1cf, v4
	v_fmac_f32_e32 v92, 0x3f317217, v4
	v_cmp_lt_f32_e64 s[82:83], |v4|, s31
	s_nop 1
	v_cndmask_b32_e64 v4, v4, v92, s[82:83]
	v_cndmask_b32_e32 v92, 0, v225, vcc
	v_cmp_gt_f32_e32 vcc, s37, v5
	v_sub_f32_e32 v4, v4, v92
	s_nop 0
	v_cndmask_b32_e64 v92, 0, 32, vcc
	v_ldexp_f32 v5, v5, v92
	v_log_f32_e32 v5, v5
	s_nop 0
	v_mul_f32_e32 v92, 0x3f317217, v5
	v_fma_f32 v92, v5, s22, -v92
	v_fmac_f32_e32 v92, 0x3377d1cf, v5
	v_fmac_f32_e32 v92, 0x3f317217, v5
	v_cmp_lt_f32_e64 s[82:83], |v5|, s31
	s_nop 1
	v_cndmask_b32_e64 v5, v5, v92, s[82:83]
	v_cndmask_b32_e32 v92, 0, v225, vcc
	v_sub_f32_e32 v5, v5, v92
	ds_write2_b32 v100, v4, v5 offset0:2 offset1:3
	v_pk_add_f32 v[4:5], v[90:91], 1.0 op_sel_hi:[1,0]
	s_nop 0
	v_div_scale_f32 v90, s[82:83], v5, v5, v57
	v_rcp_f32_e32 v91, v90
	s_nop 0
	v_fma_f32 v92, -v90, v91, 1.0
	v_fmac_f32_e32 v91, v92, v91
	v_div_scale_f32 v92, vcc, v57, v5, v57
	v_mul_f32_e32 v93, v92, v91
	v_fma_f32 v94, -v90, v93, v92
	v_fmac_f32_e32 v93, v94, v91
	v_fma_f32 v90, -v90, v93, v92
	v_div_fmas_f32 v90, v90, v91, v93
	v_div_fixup_f32 v5, v90, v5, v57
	v_div_scale_f32 v90, s[82:83], v4, v4, v56
	v_rcp_f32_e32 v91, v90
	s_nop 0
	v_fma_f32 v92, -v90, v91, 1.0
	v_fmac_f32_e32 v91, v92, v91
	v_div_scale_f32 v92, vcc, v56, v4, v56
	v_mul_f32_e32 v93, v92, v91
	v_fma_f32 v94, -v90, v93, v92
	v_fmac_f32_e32 v93, v94, v91
	v_fma_f32 v90, -v90, v93, v92
	v_div_fmas_f32 v90, v90, v91, v93
	v_div_fixup_f32 v4, v90, v4, v56
	v_pk_add_f32 v[90:91], v[32:33], v[4:5]
	s_nop 0
	v_cmp_gt_f32_e32 vcc, s37, v90
	v_pk_add_f32 v[4:5], v[90:91], 1.0 op_sel_hi:[1,0] neg_lo:[1,0] neg_hi:[1,0]
	s_nop 0
	v_cndmask_b32_e64 v92, 0, 32, vcc
	v_ldexp_f32 v90, v90, v92
	v_log_f32_e32 v90, v90
	s_nop 0
	v_mul_f32_e32 v92, 0x3f317217, v90
	v_fma_f32 v92, v90, s22, -v92
	v_fmac_f32_e32 v92, 0x3377d1cf, v90
	v_fmac_f32_e32 v92, 0x3f317217, v90
	v_cmp_lt_f32_e64 s[82:83], |v90|, s31
	s_nop 1
	v_cndmask_b32_e64 v90, v90, v92, s[82:83]
	v_cndmask_b32_e32 v92, 0, v225, vcc
	v_cmp_gt_f32_e32 vcc, s37, v91
	v_sub_f32_e32 v90, v90, v92
	s_nop 0
	v_cndmask_b32_e64 v92, 0, 32, vcc
	v_ldexp_f32 v91, v91, v92
	v_log_f32_e32 v91, v91
	s_nop 0
	v_mul_f32_e32 v92, 0x3f317217, v91
	v_fma_f32 v92, v91, s22, -v92
	v_fmac_f32_e32 v92, 0x3377d1cf, v91
	v_fmac_f32_e32 v92, 0x3f317217, v91
	v_cmp_lt_f32_e64 s[82:83], |v91|, s31
	s_nop 1
	v_cndmask_b32_e64 v91, v91, v92, s[82:83]
	v_cndmask_b32_e32 v92, 0, v225, vcc
	v_sub_f32_e32 v91, v91, v92
	ds_write2_b32 v100, v90, v91 offset0:4 offset1:5
	v_div_scale_f32 v90, s[82:83], v89, v89, v59
	v_rcp_f32_e32 v91, v90
	s_nop 0
	v_fma_f32 v92, -v90, v91, 1.0
	v_fmac_f32_e32 v91, v92, v91
	v_div_scale_f32 v92, vcc, v59, v89, v59
	v_mul_f32_e32 v93, v92, v91
	v_fma_f32 v94, -v90, v93, v92
	v_fmac_f32_e32 v93, v94, v91
	v_fma_f32 v90, -v90, v93, v92
	v_div_fmas_f32 v90, v90, v91, v93
	v_div_fixup_f32 v89, v90, v89, v59
	v_div_scale_f32 v90, s[82:83], v88, v88, v58
	v_rcp_f32_e32 v91, v90
	s_nop 0
	v_fma_f32 v92, -v90, v91, 1.0
	v_fmac_f32_e32 v91, v92, v91
	v_div_scale_f32 v92, vcc, v58, v88, v58
	v_mul_f32_e32 v93, v92, v91
	v_fma_f32 v94, -v90, v93, v92
	v_fmac_f32_e32 v93, v94, v91
	v_fma_f32 v90, -v90, v93, v92
	v_div_fmas_f32 v90, v90, v91, v93
	v_div_fixup_f32 v88, v90, v88, v58
	v_pk_add_f32 v[88:89], v[34:35], v[88:89]
	s_nop 0
	v_cmp_gt_f32_e32 vcc, s37, v88
	v_pk_add_f32 v[90:91], v[88:89], 1.0 op_sel_hi:[1,0] neg_lo:[1,0] neg_hi:[1,0]
	s_nop 0
	v_cndmask_b32_e64 v92, 0, 32, vcc
	v_ldexp_f32 v88, v88, v92
	v_log_f32_e32 v88, v88
	s_nop 0
	v_mul_f32_e32 v92, 0x3f317217, v88
	v_fma_f32 v92, v88, s22, -v92
	v_fmac_f32_e32 v92, 0x3377d1cf, v88
	v_fmac_f32_e32 v92, 0x3f317217, v88
	v_cmp_lt_f32_e64 s[82:83], |v88|, s31
	s_nop 1
	v_cndmask_b32_e64 v88, v88, v92, s[82:83]
	v_cndmask_b32_e32 v92, 0, v225, vcc
	v_cmp_gt_f32_e32 vcc, s37, v89
	v_sub_f32_e32 v88, v88, v92
	s_nop 0
	v_cndmask_b32_e64 v92, 0, 32, vcc
	v_ldexp_f32 v89, v89, v92
	v_log_f32_e32 v89, v89
	s_nop 0
	v_mul_f32_e32 v92, 0x3f317217, v89
	v_fma_f32 v92, v89, s22, -v92
	v_fmac_f32_e32 v92, 0x3377d1cf, v89
	v_fmac_f32_e32 v92, 0x3f317217, v89
	v_cmp_lt_f32_e64 s[82:83], |v89|, s31
	s_nop 1
	v_cndmask_b32_e64 v89, v89, v92, s[82:83]
	v_cndmask_b32_e32 v92, 0, v225, vcc
	v_sub_f32_e32 v89, v89, v92
	ds_write2_b32 v100, v88, v89 offset0:6 offset1:7
	v_div_scale_f32 v88, s[82:83], v19, v19, v61
	v_rcp_f32_e32 v89, v88
	s_nop 0
	v_fma_f32 v92, -v88, v89, 1.0
	v_fmac_f32_e32 v89, v92, v89
	v_div_scale_f32 v92, vcc, v61, v19, v61
	v_mul_f32_e32 v93, v92, v89
	v_fma_f32 v94, -v88, v93, v92
; DI float bflo(unsigned w) { return __uint_as_float(w << 16); }
; DI float bfhi(unsigned w) { return __uint_as_float(w & 0xffff0000u); }
; DI float hflo(unsigned w) { return (float)__builtin_bit_cast(_Float16, (u16)(w & 0xffffu)); }
; DI float hfhi(unsigned w) { return (float)__builtin_bit_cast(_Float16, (u16)(w >> 16)); }
; DI void hgrn_unit(const P& p, int l, int unit, char* lds_all) {
;     ...
;       for (int e = 0; e < 8; ++e) {
;         qv[2 * e] = bflo(qw[e]);
;         qv[2 * e + 1] = bfhi(qw[e]);
;         const float za = hflo(zw[e]), zb = hfhi(zw[e]);
;         const float fa = lbv[2 * e] + (1.f - lbv[2 * e]) / (1.f + __expf(-za));
;         const float fb = lbv[2 * e + 1] + (1.f - lbv[2 * e + 1]) / (1.f + __expf(-zb));
;         kk[2 * e] = 1.f - fa;
;         kk[2 * e + 1] = 1.f - fb;
;         Lf[tau * 65 + kc + 2 * e] = __logf(fa);
;         Lf[tau * 65 + kc + 2 * e + 1] = __logf(fb);
;         Vt[(kc + 2 * e) * 72 + tau] = (u16)(vw[e] & 0xffffu);
;         Vt[(kc + 2 * e + 1) * 72 + tau] = (u16)(vw[e] >> 16);
;       }
;     }
;     __syncthreads();
	v_fmac_f32_e32 v93, v94, v89
	v_fma_f32 v88, -v88, v93, v92
	v_div_fmas_f32 v88, v88, v89, v93
	v_div_fixup_f32 v19, v88, v19, v61
	v_div_scale_f32 v88, s[82:83], v18, v18, v60
	v_rcp_f32_e32 v89, v88
	s_nop 0
	v_fma_f32 v92, -v88, v89, 1.0
	v_fmac_f32_e32 v89, v92, v89
	v_div_scale_f32 v92, vcc, v60, v18, v60
	v_mul_f32_e32 v93, v92, v89
	v_fma_f32 v94, -v88, v93, v92
	v_fmac_f32_e32 v93, v94, v89
	v_fma_f32 v88, -v88, v93, v92
	v_div_fmas_f32 v88, v88, v89, v93
	v_div_fixup_f32 v18, v88, v18, v60
	v_pk_add_f32 v[18:19], v[36:37], v[18:19]
	s_nop 0
	v_cmp_gt_f32_e32 vcc, s37, v18
	v_pk_add_f32 v[94:95], v[18:19], 1.0 op_sel_hi:[1,0] neg_lo:[1,0] neg_hi:[1,0]
	s_nop 0
	v_cndmask_b32_e64 v88, 0, 32, vcc
	v_ldexp_f32 v18, v18, v88
	v_log_f32_e32 v18, v18
	s_nop 0
	v_mul_f32_e32 v88, 0x3f317217, v18
	v_fma_f32 v88, v18, s22, -v88
	v_fmac_f32_e32 v88, 0x3377d1cf, v18
	v_fmac_f32_e32 v88, 0x3f317217, v18
	v_cmp_lt_f32_e64 s[82:83], |v18|, s31
	s_nop 1
	v_cndmask_b32_e64 v18, v18, v88, s[82:83]
	v_cndmask_b32_e32 v88, 0, v225, vcc
	v_cmp_gt_f32_e32 vcc, s37, v19
	v_sub_f32_e32 v18, v18, v88
	s_nop 0
	v_cndmask_b32_e64 v88, 0, 32, vcc
	v_ldexp_f32 v19, v19, v88
	v_log_f32_e32 v19, v19
	s_nop 0
	v_mul_f32_e32 v88, 0x3f317217, v19
	v_fma_f32 v88, v19, s22, -v88
	v_fmac_f32_e32 v88, 0x3377d1cf, v19
	v_fmac_f32_e32 v88, 0x3f317217, v19
	v_cmp_lt_f32_e64 s[82:83], |v19|, s31
	s_nop 1
	v_cndmask_b32_e64 v19, v19, v88, s[82:83]
	v_cndmask_b32_e32 v88, 0, v225, vcc
	v_sub_f32_e32 v19, v19, v88
	ds_write2_b32 v100, v18, v19 offset0:8 offset1:9
	v_div_scale_f32 v18, s[82:83], v17, v17, v63
	v_rcp_f32_e32 v19, v18
	s_nop 0
	v_fma_f32 v88, -v18, v19, 1.0
	v_fmac_f32_e32 v19, v88, v19
	v_div_scale_f32 v88, vcc, v63, v17, v63
	v_mul_f32_e32 v89, v88, v19
	v_fma_f32 v92, -v18, v89, v88
	v_fmac_f32_e32 v89, v92, v19
	v_fma_f32 v18, -v18, v89, v88
	v_div_fmas_f32 v18, v18, v19, v89
	v_div_fixup_f32 v17, v18, v17, v63
	v_div_scale_f32 v18, s[82:83], v16, v16, v62
	v_rcp_f32_e32 v19, v18
	s_nop 0
	v_fma_f32 v88, -v18, v19, 1.0
	v_fmac_f32_e32 v19, v88, v19
	v_div_scale_f32 v88, vcc, v62, v16, v62
	v_mul_f32_e32 v89, v88, v19
	v_fma_f32 v92, -v18, v89, v88
	v_fmac_f32_e32 v89, v92, v19
	v_fma_f32 v18, -v18, v89, v88
	v_div_fmas_f32 v18, v18, v19, v89
	v_div_fixup_f32 v16, v18, v16, v62
	v_pk_add_f32 v[16:17], v[38:39], v[16:17]
	s_nop 0
	v_cmp_gt_f32_e32 vcc, s37, v16
	v_pk_add_f32 v[96:97], v[16:17], 1.0 op_sel_hi:[1,0] neg_lo:[1,0] neg_hi:[1,0]
	s_nop 0
	v_cndmask_b32_e64 v18, 0, 32, vcc
	v_ldexp_f32 v16, v16, v18
	v_log_f32_e32 v16, v16
	s_nop 0
	v_mul_f32_e32 v18, 0x3f317217, v16
	v_fma_f32 v18, v16, s22, -v18
	v_fmac_f32_e32 v18, 0x3377d1cf, v16
	v_fmac_f32_e32 v18, 0x3f317217, v16
	v_cmp_lt_f32_e64 s[82:83], |v16|, s31
	s_nop 1
	v_cndmask_b32_e64 v16, v16, v18, s[82:83]
	v_cndmask_b32_e32 v18, 0, v225, vcc
	v_cmp_gt_f32_e32 vcc, s37, v17
	v_sub_f32_e32 v16, v16, v18
	s_nop 0
	v_cndmask_b32_e64 v18, 0, 32, vcc
	v_ldexp_f32 v17, v17, v18
	v_log_f32_e32 v17, v17
	s_nop 0
	v_mul_f32_e32 v18, 0x3f317217, v17
	v_fma_f32 v18, v17, s22, -v18
	v_fmac_f32_e32 v18, 0x3377d1cf, v17
	v_fmac_f32_e32 v18, 0x3f317217, v17
	v_cmp_lt_f32_e64 s[82:83], |v17|, s31
	s_nop 1
	v_cndmask_b32_e64 v17, v17, v18, s[82:83]
	v_cndmask_b32_e32 v18, 0, v225, vcc
	v_sub_f32_e32 v17, v17, v18
	ds_write2_b32 v100, v16, v17 offset0:10 offset1:11
	v_div_scale_f32 v16, s[82:83], v11, v11, v65
	v_rcp_f32_e32 v17, v16
	s_nop 0
	v_fma_f32 v18, -v16, v17, 1.0
	v_fmac_f32_e32 v17, v18, v17
	v_div_scale_f32 v18, vcc, v65, v11, v65
	v_mul_f32_e32 v19, v18, v17
	v_fma_f32 v88, -v16, v19, v18
	v_fmac_f32_e32 v19, v88, v17
	v_fma_f32 v16, -v16, v19, v18
	v_div_fmas_f32 v16, v16, v17, v19
	v_div_fixup_f32 v11, v16, v11, v65
	v_div_scale_f32 v16, s[82:83], v10, v10, v64
	v_rcp_f32_e32 v17, v16
	s_nop 0
	v_fma_f32 v18, -v16, v17, 1.0
	v_fmac_f32_e32 v17, v18, v17
	v_div_scale_f32 v18, vcc, v64, v10, v64
	v_mul_f32_e32 v19, v18, v17
	v_fma_f32 v88, -v16, v19, v18
	v_fmac_f32_e32 v19, v88, v17
	v_fma_f32 v16, -v16, v19, v18
	v_div_fmas_f32 v16, v16, v17, v19
	v_div_fixup_f32 v10, v16, v10, v64
	v_pk_add_f32 v[10:11], v[40:41], v[10:11]
	s_nop 0
	v_cmp_gt_f32_e32 vcc, s37, v10
	v_pk_add_f32 v[92:93], v[10:11], 1.0 op_sel_hi:[1,0] neg_lo:[1,0] neg_hi:[1,0]
	s_nop 0
	v_cndmask_b32_e64 v16, 0, 32, vcc
	v_ldexp_f32 v10, v10, v16
	v_log_f32_e32 v10, v10
	s_nop 0
	v_mul_f32_e32 v16, 0x3f317217, v10
	v_fma_f32 v16, v10, s22, -v16
	v_fmac_f32_e32 v16, 0x3377d1cf, v10
	v_fmac_f32_e32 v16, 0x3f317217, v10
	v_cmp_lt_f32_e64 s[82:83], |v10|, s31
	s_nop 1
	v_cndmask_b32_e64 v10, v10, v16, s[82:83]
	v_cndmask_b32_e32 v16, 0, v225, vcc
	v_cmp_gt_f32_e32 vcc, s37, v11
	v_sub_f32_e32 v10, v10, v16
	s_nop 0
	v_cndmask_b32_e64 v16, 0, 32, vcc
	v_ldexp_f32 v11, v11, v16
	v_log_f32_e32 v11, v11
	s_nop 0
	v_mul_f32_e32 v16, 0x3f317217, v11
	v_fma_f32 v16, v11, s22, -v16
	v_fmac_f32_e32 v16, 0x3377d1cf, v11
	v_fmac_f32_e32 v16, 0x3f317217, v11
	v_cmp_lt_f32_e64 s[82:83], |v11|, s31
	s_nop 1
	v_cndmask_b32_e64 v11, v11, v16, s[82:83]
	v_cndmask_b32_e32 v16, 0, v225, vcc
	v_sub_f32_e32 v11, v11, v16
	ds_write2_b32 v100, v10, v11 offset0:12 offset1:13
	v_div_scale_f32 v10, s[82:83], v9, v9, v67
	v_rcp_f32_e32 v11, v10
	s_nop 0
	v_fma_f32 v16, -v10, v11, 1.0
	v_fmac_f32_e32 v11, v16, v11
	v_div_scale_f32 v16, vcc, v67, v9, v67
	v_mul_f32_e32 v17, v16, v11
	v_fma_f32 v18, -v10, v17, v16
	v_fmac_f32_e32 v17, v18, v11
	v_fma_f32 v10, -v10, v17, v16
	v_div_fmas_f32 v10, v10, v11, v17
	v_div_fixup_f32 v9, v10, v9, v67
	v_div_scale_f32 v10, s[82:83], v8, v8, v66
	v_rcp_f32_e32 v11, v10
	s_nop 0
	v_fma_f32 v16, -v10, v11, 1.0
	v_fmac_f32_e32 v11, v16, v11
	v_div_scale_f32 v16, vcc, v66, v8, v66
	v_mul_f32_e32 v17, v16, v11
	v_fma_f32 v18, -v10, v17, v16
	v_fmac_f32_e32 v17, v18, v11
	v_fma_f32 v10, -v10, v17, v16
	v_div_fmas_f32 v10, v10, v11, v17
	v_div_fixup_f32 v8, v10, v8, v66
	v_pk_add_f32 v[8:9], v[42:43], v[8:9]
	v_add_u32_e32 v11, 0x400, v118
	v_cmp_gt_f32_e32 vcc, s37, v8
	v_pk_add_f32 v[88:89], v[8:9], 1.0 op_sel_hi:[1,0] neg_lo:[1,0] neg_hi:[1,0]
	s_nop 0
	v_cndmask_b32_e64 v10, 0, 32, vcc
	v_ldexp_f32 v8, v8, v10
	v_log_f32_e32 v8, v8
	s_nop 0
	v_mul_f32_e32 v10, 0x3f317217, v8
	v_fma_f32 v10, v8, s22, -v10
	v_fmac_f32_e32 v10, 0x3377d1cf, v8
	v_fmac_f32_e32 v10, 0x3f317217, v8
	v_cmp_lt_f32_e64 s[82:83], |v8|, s31
	s_nop 1
	v_cndmask_b32_e64 v8, v8, v10, s[82:83]
	v_cndmask_b32_e32 v10, 0, v225, vcc
	v_cmp_gt_f32_e32 vcc, s37, v9
	v_sub_f32_e32 v8, v8, v10
	s_nop 0
	v_cndmask_b32_e64 v10, 0, 32, vcc
	v_ldexp_f32 v9, v9, v10
	v_log_f32_e32 v9, v9
	s_nop 0
	v_mul_f32_e32 v10, 0x3f317217, v9
	v_fma_f32 v10, v9, s22, -v10
	v_fmac_f32_e32 v10, 0x3377d1cf, v9
	v_fmac_f32_e32 v10, 0x3f317217, v9
	v_cmp_lt_f32_e64 s[82:83], |v9|, s31
	s_nop 1
	v_cndmask_b32_e64 v9, v9, v10, s[82:83]
	v_cndmask_b32_e32 v10, 0, v225, vcc
	v_sub_f32_e32 v9, v9, v10
	ds_write2_b32 v100, v8, v9 offset0:14 offset1:15
	s_waitcnt lgkmcnt(0)
	s_barrier
; DI u16 f2bf(float x) { return (u16)pack2(x, 0.f); }
; DI void hgrn_unit(const P& p, int l, int unit, char* lds_all) {
;     ...
;     {
;       const int k = tid & 63, sg = tid >> 6;
;       float run = 0.f;
; #pragma unroll
;       for (int i = 0; i < 16; ++i) {
;         float* ptr = &Lf[(sg * 16 + i) * 65 + k];
;         run += *ptr;
;         *ptr = run;
;       }
;       Seg[sg * 64 + k] = run;
;     }
;     __syncthreads();
;     {
;       const int sg = tau >> 4;
;       unsigned qmw[8], kmw[8];
; #pragma unroll
;       for (int e = 0; e < 8; ++e) {
;         float qq[2], km2[2];
; #pragma unroll
;         for (int u = 0; u < 2; ++u) {
;           const int i = 2 * e + u, k = kc + i;
;           const float s0 = Seg[k], s1 = Seg[64 + k], s2 = Seg[128 + k];
;           const float off = (sg > 0 ? s0 : 0.f) + (sg > 1 ? s1 : 0.f) + (sg > 2 ? s2 : 0.f);
;           const float bc = Lf[tau * 65 + k] + off;
;           const float rr = Lf[31 * 65 + k] + s0;
;           qq[u] = qv[i] * __expf(bc - rr);
;           km2[u] = kk[i] * __expf(rr - bc);
;           KmT[k * 72 + tau] = f2bf(km2[u]);
;         }
;         qmw[e] = pack2(qq[0], qq[1]);
;         kmw[e] = pack2(km2[0], km2[1]);
;       }
	ds_read2_b32 v[8:9], v118 offset1:65
	s_waitcnt lgkmcnt(0)
	v_add_f32_e32 v8, 0, v8
	v_add_f32_e32 v10, v8, v9
	ds_write2_b32 v118, v8, v10 offset1:65
	ds_read2_b32 v[8:9], v118 offset0:130 offset1:195
	s_waitcnt lgkmcnt(0)
	v_add_f32_e32 v8, v10, v8
	v_add_f32_e32 v10, v8, v9
	ds_write2_b32 v118, v8, v10 offset0:130 offset1:195
	ds_read2_b32 v[8:9], v11 offset0:4 offset1:69
	s_waitcnt lgkmcnt(0)
	v_add_f32_e32 v8, v10, v8
	v_add_f32_e32 v10, v8, v9
	ds_write2_b32 v11, v8, v10 offset0:4 offset1:69
	ds_read2_b32 v[8:9], v11 offset0:134 offset1:199
	s_waitcnt lgkmcnt(0)
	v_add_f32_e32 v8, v10, v8
	v_add_f32_e32 v10, v8, v9
	ds_write2_b32 v11, v8, v10 offset0:134 offset1:199
	v_add_u32_e32 v11, 0x800, v118
	ds_read2_b32 v[8:9], v11 offset0:8 offset1:73
	s_waitcnt lgkmcnt(0)
	v_add_f32_e32 v8, v10, v8
	v_add_f32_e32 v10, v8, v9
	ds_write2_b32 v11, v8, v10 offset0:8 offset1:73
	ds_read2_b32 v[8:9], v11 offset0:138 offset1:203
	s_waitcnt lgkmcnt(0)
	v_add_f32_e32 v8, v10, v8
	v_add_f32_e32 v10, v8, v9
	ds_write2_b32 v11, v8, v10 offset0:138 offset1:203
	v_add_u32_e32 v11, 0xc00, v118
	ds_read2_b32 v[8:9], v11 offset0:12 offset1:77
	s_waitcnt lgkmcnt(0)
	v_add_f32_e32 v8, v10, v8
	v_add_f32_e32 v10, v8, v9
	ds_write2_b32 v11, v8, v10 offset0:12 offset1:77
	ds_read2_b32 v[8:9], v11 offset0:142 offset1:207
	s_waitcnt lgkmcnt(0)
	v_add_f32_e32 v8, v10, v8
	v_add_f32_e32 v9, v8, v9
	ds_write2_b32 v11, v8, v9 offset0:142 offset1:207
	ds_write_b32 v101, v9 offset:16640
	s_waitcnt lgkmcnt(0)
	s_barrier
	ds_read_b128 v[16:19], v112 offset:16640
	ds_read_b128 v[8:11], v112 offset:16656
	ds_read_b128 v[128:131], v112 offset:16896
	ds_read_b128 v[132:135], v112 offset:17152
	ds_read2_b32 v[138:139], v100 offset1:1
	s_waitcnt lgkmcnt(4)
	v_cndmask_b32_e64 v136, v16, 0, s[42:43]
	v_mov_b32_e32 v142, v16
	s_waitcnt lgkmcnt(2)
	v_cndmask_b32_e64 v128, 0, v128, s[44:45]
	v_add_f32_e32 v128, v136, v128
	s_waitcnt lgkmcnt(1)
	v_cndmask_b32_e64 v132, 0, v132, s[46:47]
	v_add_f32_e32 v137, v128, v132
	v_add_u32_e32 v128, 0x1f7c, v112
	ds_read2_b32 v[140:141], v128 offset1:1
	v_cndmask_b32_e64 v132, v17, 0, s[42:43]
	v_cndmask_b32_e64 v129, 0, v129, s[44:45]
	v_add_f32_e32 v129, v132, v129
	v_cndmask_b32_e64 v132, 0, v133, s[46:47]
	s_waitcnt lgkmcnt(1)
	v_mov_b32_e32 v143, v138
	s_waitcnt lgkmcnt(0)
	v_mov_b32_e32 v136, v140
	v_add_f32_e32 v133, v129, v132
	v_mov_b32_e32 v138, v17
	v_mov_b32_e32 v132, v141
	v_pk_add_f32 v[136:137], v[142:143], v[136:137]
	v_pk_add_f32 v[132:133], v[138:139], v[132:133]
	v_sub_f32_e32 v128, v136, v137
	v_sub_f32_e32 v17, v132, v133
	v_mul_f32_e32 v128, 0x3fb8aa3b, v128
	v_mul_f32_e32 v17, 0x3fb8aa3b, v17
	v_exp_f32_e32 v128, v128
	v_exp_f32_e32 v129, v17
	v_sub_f32_e32 v16, v137, v136
	v_mul_f32_e32 v16, 0x3fb8aa3b, v16
	v_exp_f32_e32 v16, v16
	v_pk_mul_f32 v[2:3], v[2:3], v[128:129]
	ds_read2_b32 v[128:129], v100 offset0:2 offset1:3
	v_cvt_pk_bf16_f32 v17, v2, s0
	ds_write_b16 v119, v17 offset:36096
	v_sub_f32_e32 v17, v133, v132
	v_mul_f32_e32 v17, 0x3fb8aa3b, v17
	v_exp_f32_e32 v17, v17
	v_cvt_pk_bf16_f32 v2, v2, v3
	v_mov_b32_e32 v136, v18
	v_pk_mul_f32 v[6:7], v[16:17], v[6:7]
	v_cvt_pk_bf16_f32 v16, v3, s0
	v_cvt_pk_bf16_f32 v6, v6, v7
	v_cndmask_b32_e64 v3, v18, 0, s[42:43]
	v_cndmask_b32_e64 v7, 0, v130, s[44:45]
	v_add_f32_e32 v3, v3, v7
	v_cndmask_b32_e64 v7, 0, v134, s[46:47]
	v_add_f32_e32 v17, v3, v7
	v_add_u32_e32 v3, 0x1f84, v112
	ds_read2_b32 v[132:133], v3 offset1:1
	ds_write_b16 v119, v16 offset:36240
	s_waitcnt lgkmcnt(3)
	v_mov_b32_e32 v137, v128
	v_cndmask_b32_e64 v7, 0, v131, s[44:45]
	v_mov_b32_e32 v128, v19
	s_waitcnt lgkmcnt(1)
	v_mov_b32_e32 v16, v132
	v_pk_add_f32 v[16:17], v[136:137], v[16:17]
	v_mov_b32_e32 v130, v133
	v_sub_f32_e32 v3, v17, v16
	v_mul_f32_e32 v3, 0x3fb8aa3b, v3
	v_exp_f32_e32 v18, v3
	v_sub_f32_e32 v3, v16, v17
	v_mul_f32_e32 v3, 0x3fb8aa3b, v3
	v_exp_f32_e32 v16, v3
	v_cndmask_b32_e64 v3, v19, 0, s[42:43]
	v_add_f32_e32 v3, v3, v7
	v_cndmask_b32_e64 v7, 0, v135, s[46:47]
	v_add_f32_e32 v131, v3, v7
	v_pk_add_f32 v[128:129], v[128:129], v[130:131]
	v_mov_b32_e32 v134, v8
	v_sub_f32_e32 v3, v128, v129
	v_mul_f32_e32 v3, 0x3fb8aa3b, v3
	v_exp_f32_e32 v17, v3
	s_nop 0
	v_pk_mul_f32 v[14:15], v[14:15], v[16:17]
	s_nop 0
	v_cvt_pk_bf16_f32 v3, v14, s0
	ds_write_b16 v119, v3 offset:36384
	v_sub_f32_e32 v3, v129, v128
	v_mul_f32_e32 v3, 0x3fb8aa3b, v3
	v_exp_f32_e32 v19, v3
	v_cvt_pk_bf16_f32 v3, v15, s0
	ds_write_b16 v119, v3 offset:36528
	v_cvt_pk_bf16_f32 v3, v14, v15
	v_pk_mul_f32 v[12:13], v[18:19], v[12:13]
	v_cndmask_b32_e64 v128, v8, 0, s[42:43]
	v_cvt_pk_bf16_f32 v7, v12, v13
	ds_read_b128 v[12:15], v112 offset:16912
	ds_read_b128 v[16:19], v112 offset:17168
	ds_read2_b32 v[130:131], v100 offset0:4 offset1:5
	s_waitcnt lgkmcnt(2)
	v_cndmask_b32_e64 v12, 0, v12, s[44:45]
	v_add_f32_e32 v12, v128, v12
	s_waitcnt lgkmcnt(1)
	v_cndmask_b32_e64 v16, 0, v16, s[46:47]
	v_add_f32_e32 v129, v12, v16
	v_add_u32_e32 v12, 0x1f8c, v112
	ds_read2_b32 v[132:133], v12 offset1:1
	v_cndmask_b32_e64 v16, v9, 0, s[42:43]
	v_cndmask_b32_e64 v13, 0, v13, s[44:45]
	v_add_f32_e32 v13, v16, v13
	v_cndmask_b32_e64 v16, 0, v17, s[46:47]
	s_waitcnt lgkmcnt(1)
	v_mov_b32_e32 v135, v130
	s_waitcnt lgkmcnt(0)
; DI u16 f2bf(float x) { return (u16)pack2(x, 0.f); }
; DI void hgrn_unit(const P& p, int l, int unit, char* lds_all) {
;     ...
;     {
;       const int sg = tau >> 4;
;       unsigned qmw[8], kmw[8];
; #pragma unroll
;       for (int e = 0; e < 8; ++e) {
;         float qq[2], km2[2];
; #pragma unroll
;         for (int u = 0; u < 2; ++u) {
;           const int i = 2 * e + u, k = kc + i;
;           const float s0 = Seg[k], s1 = Seg[64 + k], s2 = Seg[128 + k];
;           const float off = (sg > 0 ? s0 : 0.f) + (sg > 1 ? s1 : 0.f) + (sg > 2 ? s2 : 0.f);
;           const float bc = Lf[tau * 65 + k] + off;
;           const float rr = Lf[31 * 65 + k] + s0;
;           qq[u] = qv[i] * __expf(bc - rr);
;           km2[u] = kk[i] * __expf(rr - bc);
;           KmT[k * 72 + tau] = f2bf(km2[u]);
;         }
;         qmw[e] = pack2(qq[0], qq[1]);
;         kmw[e] = pack2(km2[0], km2[1]);
;       }
	v_mov_b32_e32 v128, v132
	v_add_f32_e32 v17, v13, v16
	v_mov_b32_e32 v130, v9
	v_mov_b32_e32 v16, v133
	v_pk_add_f32 v[128:129], v[134:135], v[128:129]
	v_pk_add_f32 v[16:17], v[130:131], v[16:17]
	v_sub_f32_e32 v12, v128, v129
	v_sub_f32_e32 v9, v16, v17
	v_mul_f32_e32 v12, 0x3fb8aa3b, v12
	v_mul_f32_e32 v9, 0x3fb8aa3b, v9
	v_exp_f32_e32 v12, v12
	v_exp_f32_e32 v13, v9
	v_sub_f32_e32 v8, v129, v128
	v_mul_f32_e32 v8, 0x3fb8aa3b, v8
	v_exp_f32_e32 v8, v8
	v_pk_mul_f32 v[4:5], v[4:5], v[12:13]
	v_mov_b32_e32 v128, v10
	v_cvt_pk_bf16_f32 v9, v4, s0
	ds_write_b16 v119, v9 offset:36672
	v_sub_f32_e32 v9, v17, v16
	v_mul_f32_e32 v9, 0x3fb8aa3b, v9
	v_exp_f32_e32 v9, v9
	v_cvt_pk_bf16_f32 v12, v5, s0
	v_cvt_pk_bf16_f32 v4, v4, v5
	v_cndmask_b32_e64 v5, v10, 0, s[42:43]
	v_pk_mul_f32 v[8:9], v[8:9], v[26:27]
	ds_read2_b32 v[16:17], v100 offset0:6 offset1:7
	v_cvt_pk_bf16_f32 v8, v8, v9
	v_cndmask_b32_e64 v9, 0, v14, s[44:45]
	v_add_f32_e32 v5, v5, v9
	v_cndmask_b32_e64 v9, 0, v18, s[46:47]
	v_add_f32_e32 v13, v5, v9
	v_add_u32_e32 v5, 0x1f94, v112
	ds_read2_b32 v[26:27], v5 offset1:1
	ds_write_b16 v119, v12 offset:36816
	s_waitcnt lgkmcnt(2)
	v_mov_b32_e32 v129, v16
	v_cndmask_b32_e64 v9, 0, v15, s[44:45]
	v_mov_b32_e32 v16, v11
	s_waitcnt lgkmcnt(1)
	v_mov_b32_e32 v12, v26
	v_pk_add_f32 v[12:13], v[128:129], v[12:13]
	v_mov_b32_e32 v14, v27
	v_sub_f32_e32 v5, v13, v12
	v_mul_f32_e32 v5, 0x3fb8aa3b, v5
	v_exp_f32_e32 v10, v5
	v_sub_f32_e32 v5, v12, v13
	v_mul_f32_e32 v5, 0x3fb8aa3b, v5
	v_exp_f32_e32 v12, v5
	v_cndmask_b32_e64 v5, v11, 0, s[42:43]
	v_add_f32_e32 v5, v5, v9
	v_cndmask_b32_e64 v9, 0, v19, s[46:47]
	v_add_f32_e32 v15, v5, v9
	v_pk_add_f32 v[14:15], v[16:17], v[14:15]
	s_nop 0
	v_sub_f32_e32 v5, v14, v15
	v_mul_f32_e32 v5, 0x3fb8aa3b, v5
	v_exp_f32_e32 v13, v5
	s_nop 0
	v_pk_mul_f32 v[12:13], v[90:91], v[12:13]
	s_nop 0
	v_cvt_pk_bf16_f32 v5, v12, s0
	ds_write_b16 v119, v5 offset:36960
	v_sub_f32_e32 v5, v15, v14
	v_mul_f32_e32 v5, 0x3fb8aa3b, v5
	v_exp_f32_e32 v11, v5
	v_cvt_pk_bf16_f32 v5, v13, s0
	ds_write_b16 v119, v5 offset:37104
	v_cvt_pk_bf16_f32 v5, v12, v13
	v_pk_mul_f32 v[10:11], v[10:11], v[24:25]
	s_nop 0
	v_cvt_pk_bf16_f32 v9, v10, v11
	ds_read_b128 v[10:13], v112 offset:16672
	ds_read_b128 v[16:19], v112 offset:16688
	ds_read_b128 v[24:27], v112 offset:16928
	ds_read_b128 v[128:131], v112 offset:17184
	ds_read2_b32 v[90:91], v100 offset0:8 offset1:9
	s_waitcnt lgkmcnt(4)
	v_cndmask_b32_e64 v14, v10, 0, s[42:43]
	v_mov_b32_e32 v134, v10
	s_waitcnt lgkmcnt(2)
	v_cndmask_b32_e64 v15, 0, v24, s[44:45]
	v_add_f32_e32 v14, v14, v15
	s_waitcnt lgkmcnt(1)
	v_cndmask_b32_e64 v15, 0, v128, s[46:47]
	v_add_f32_e32 v15, v14, v15
	v_add_u32_e32 v14, 0x1f9c, v112
	ds_read2_b32 v[132:133], v14 offset1:1
	s_waitcnt lgkmcnt(1)
	v_mov_b32_e32 v135, v90
	v_cndmask_b32_e64 v24, 0, v25, s[44:45]
	v_mov_b32_e32 v90, v11
	s_waitcnt lgkmcnt(0)
	v_mov_b32_e32 v14, v132
	v_pk_add_f32 v[14:15], v[134:135], v[14:15]
	s_nop 0
	v_sub_f32_e32 v10, v15, v14
	v_sub_f32_e32 v14, v14, v15
	v_cndmask_b32_e64 v15, v11, 0, s[42:43]
	v_add_f32_e32 v15, v15, v24
	v_cndmask_b32_e64 v24, 0, v129, s[46:47]
	v_add_f32_e32 v25, v15, v24
	v_mov_b32_e32 v24, v133
	v_pk_add_f32 v[24:25], v[90:91], v[24:25]
	v_mul_f32_e32 v14, 0x3fb8aa3b, v14
	v_sub_f32_e32 v11, v24, v25
	v_mul_f32_e32 v11, 0x3fb8aa3b, v11
	v_exp_f32_e32 v14, v14
	v_exp_f32_e32 v15, v11
	v_mul_f32_e32 v10, 0x3fb8aa3b, v10
	v_exp_f32_e32 v10, v10
	v_pk_mul_f32 v[90:91], v[94:95], v[14:15]
	s_nop 0
	v_cvt_pk_bf16_f32 v11, v90, s0
	ds_write_b16 v119, v11 offset:37248
	v_sub_f32_e32 v11, v25, v24
	v_mul_f32_e32 v11, 0x3fb8aa3b, v11
	v_exp_f32_e32 v11, v11
	v_cvt_pk_bf16_f32 v14, v91, s0
	ds_write_b16 v119, v14 offset:37392
	v_cndmask_b32_e64 v15, 0, v26, s[44:45]
	v_pk_mul_f32 v[10:11], v[10:11], v[22:23]
	ds_read2_b32 v[24:25], v100 offset0:10 offset1:11
	v_cvt_pk_bf16_f32 v14, v10, v11
	v_cndmask_b32_e64 v11, v12, 0, s[42:43]
	v_add_f32_e32 v11, v11, v15
	v_cndmask_b32_e64 v15, 0, v130, s[46:47]
	v_add_f32_e32 v23, v11, v15
	v_add_u32_e32 v11, 0x1fa4, v112
	v_cvt_pk_bf16_f32 v10, v90, v91
	ds_read2_b32 v[90:91], v11 offset1:1
	v_mov_b32_e32 v94, v12
	s_waitcnt lgkmcnt(1)
	v_mov_b32_e32 v95, v24
	v_cndmask_b32_e64 v15, 0, v27, s[44:45]
	v_mov_b32_e32 v24, v13
	s_waitcnt lgkmcnt(0)
	v_mov_b32_e32 v22, v90
	v_pk_add_f32 v[22:23], v[94:95], v[22:23]
	v_mov_b32_e32 v26, v91
	v_sub_f32_e32 v11, v23, v22
	v_mul_f32_e32 v11, 0x3fb8aa3b, v11
	v_exp_f32_e32 v12, v11
	v_sub_f32_e32 v11, v22, v23
	v_mul_f32_e32 v11, 0x3fb8aa3b, v11
	v_exp_f32_e32 v22, v11
	v_cndmask_b32_e64 v11, v13, 0, s[42:43]
	v_add_f32_e32 v11, v11, v15
	v_cndmask_b32_e64 v15, 0, v131, s[46:47]
	v_add_f32_e32 v27, v11, v15
	v_pk_add_f32 v[24:25], v[24:25], v[26:27]
	s_nop 0
	v_sub_f32_e32 v11, v24, v25
	v_mul_f32_e32 v11, 0x3fb8aa3b, v11
	v_exp_f32_e32 v23, v11
	s_nop 0
	v_pk_mul_f32 v[22:23], v[96:97], v[22:23]
	s_nop 0
	v_cvt_pk_bf16_f32 v11, v22, s0
	ds_write_b16 v119, v11 offset:37536
	v_sub_f32_e32 v11, v25, v24
	v_mul_f32_e32 v11, 0x3fb8aa3b, v11
	v_exp_f32_e32 v13, v11
	v_cvt_pk_bf16_f32 v11, v23, s0
	ds_write_b16 v119, v11 offset:37680
	v_cvt_pk_bf16_f32 v11, v22, v23
	v_pk_mul_f32 v[12:13], v[12:13], v[20:21]
	ds_read_b128 v[20:23], v112 offset:16944
	ds_read_b128 v[24:27], v112 offset:17200
	v_cvt_pk_bf16_f32 v15, v12, v13
	v_cndmask_b32_e64 v12, v16, 0, s[42:43]
	ds_read2_b32 v[90:91], v100 offset0:12 offset1:13
	s_waitcnt lgkmcnt(2)
	v_cndmask_b32_e64 v13, 0, v20, s[44:45]
	v_add_f32_e32 v12, v12, v13
	s_waitcnt lgkmcnt(1)
	v_cndmask_b32_e64 v13, 0, v24, s[46:47]
	v_add_f32_e32 v13, v12, v13
	v_add_u32_e32 v12, 0x1fac, v112
	ds_read2_b32 v[94:95], v12 offset1:1
	v_mov_b32_e32 v96, v16
	s_waitcnt lgkmcnt(1)
; DI u16 f2bf(float x) { return (u16)pack2(x, 0.f); }
; DI void hgrn_unit(const P& p, int l, int unit, char* lds_all) {
;     ...
;       *(uint4*)&Qm[tau * 72 + kc] = make_uint4(qmw[0], qmw[1], qmw[2], qmw[3]);
;       *(uint4*)&Qm[tau * 72 + kc + 8] = make_uint4(qmw[4], qmw[5], qmw[6], qmw[7]);
;       *(uint4*)&Km[tau * 72 + kc] = make_uint4(kmw[0], kmw[1], kmw[2], kmw[3]);
;       *(uint4*)&Km[tau * 72 + kc + 8] = make_uint4(kmw[4], kmw[5], kmw[6], kmw[7]);
; #pragma unroll
;       for (int nt = 0; nt < 4; ++nt) {
;         const int k = nt * 16 + r;
;         const float er = __expf(Lf[31 * 65 + k] + Seg[k]);
; #pragma unroll
;         for (int j = 0; j < 4; ++j) St[(w * 16 + g * 4 + j) * 72 + k] = f2bf(Sacc[nt][j] * er);
;       }
;     }
;     __syncthreads();
	v_mov_b32_e32 v97, v90
	v_cndmask_b32_e64 v20, 0, v21, s[44:45]
	v_mov_b32_e32 v90, v17
	s_waitcnt lgkmcnt(0)
	v_mov_b32_e32 v12, v94
	v_pk_add_f32 v[12:13], v[96:97], v[12:13]
	v_add_u32_e32 v96, v127, v115
	v_sub_f32_e32 v16, v13, v12
	v_sub_f32_e32 v12, v12, v13
	v_cndmask_b32_e64 v13, v17, 0, s[42:43]
	v_add_f32_e32 v13, v13, v20
	v_cndmask_b32_e64 v20, 0, v25, s[46:47]
	v_add_f32_e32 v21, v13, v20
	v_mov_b32_e32 v20, v95
	v_pk_add_f32 v[20:21], v[90:91], v[20:21]
	v_mul_f32_e32 v12, 0x3fb8aa3b, v12
	v_sub_f32_e32 v13, v20, v21
	v_mul_f32_e32 v13, 0x3fb8aa3b, v13
	v_exp_f32_e32 v12, v12
	v_exp_f32_e32 v13, v13
	v_mul_f32_e32 v16, 0x3fb8aa3b, v16
	v_exp_f32_e32 v16, v16
	ds_read2_b32 v[24:25], v100 offset0:14 offset1:15
	v_pk_mul_f32 v[12:13], v[92:93], v[12:13]
	v_mov_b32_e32 v90, v18
	v_cvt_pk_bf16_f32 v17, v12, s0
	ds_write_b16 v119, v17 offset:37824
	v_sub_f32_e32 v17, v21, v20
	v_mul_f32_e32 v17, 0x3fb8aa3b, v17
	v_exp_f32_e32 v17, v17
	v_cvt_pk_bf16_f32 v20, v13, s0
	v_cvt_pk_bf16_f32 v12, v12, v13
	v_cndmask_b32_e64 v13, v18, 0, s[42:43]
	v_pk_mul_f32 v[16:17], v[16:17], v[86:87]
	ds_write_b16 v119, v20 offset:37968
	v_cvt_pk_bf16_f32 v16, v16, v17
	v_cndmask_b32_e64 v17, 0, v22, s[44:45]
	v_add_f32_e32 v13, v13, v17
	v_cndmask_b32_e64 v17, 0, v26, s[46:47]
	v_add_f32_e32 v21, v13, v17
	v_add_u32_e32 v13, 0x1fb4, v112
	ds_read2_b32 v[86:87], v13 offset1:1
	s_waitcnt lgkmcnt(3)
	v_mov_b32_e32 v91, v24
	v_cndmask_b32_e64 v17, 0, v23, s[44:45]
	v_mov_b32_e32 v24, v19
	v_add_u32_e32 v26, v127, v114
	s_waitcnt lgkmcnt(0)
	v_mov_b32_e32 v20, v86
	v_pk_add_f32 v[20:21], v[90:91], v[20:21]
	v_mov_b32_e32 v22, v87
	v_sub_f32_e32 v13, v21, v20
	v_mul_f32_e32 v13, 0x3fb8aa3b, v13
	v_exp_f32_e32 v18, v13
	v_sub_f32_e32 v13, v20, v21
	v_mul_f32_e32 v13, 0x3fb8aa3b, v13
	v_exp_f32_e32 v20, v13
	v_cndmask_b32_e64 v13, v19, 0, s[42:43]
	v_add_f32_e32 v13, v13, v17
	v_cndmask_b32_e64 v17, 0, v27, s[46:47]
	v_add_f32_e32 v23, v13, v17
	v_pk_add_f32 v[22:23], v[24:25], v[22:23]
	v_ashrrev_i32_e32 v27, 31, v26
	v_sub_f32_e32 v13, v22, v23
	v_mul_f32_e32 v13, 0x3fb8aa3b, v13
	v_exp_f32_e32 v21, v13
	v_lshlrev_b64 v[26:27], 8, v[26:27]
	v_ashrrev_i32_e32 v97, 31, v96
	v_lshl_add_u64 v[26:27], v[50:51], 0, v[26:27]
	v_pk_mul_f32 v[20:21], v[88:89], v[20:21]
	v_lshlrev_b64 v[96:97], 8, v[96:97]
	v_cvt_pk_bf16_f32 v13, v20, s0
	ds_write_b16 v119, v13 offset:38112
	v_sub_f32_e32 v13, v23, v22
	v_mul_f32_e32 v13, 0x3fb8aa3b, v13
	v_exp_f32_e32 v19, v13
	v_cvt_pk_bf16_f32 v13, v21, s0
	ds_write_b16 v119, v13 offset:38256
	v_cvt_pk_bf16_f32 v13, v20, v21
	v_pk_mul_f32 v[18:19], v[18:19], v[84:85]
	v_lshl_add_u64 v[96:97], v[50:51], 0, v[96:97]
	v_cvt_pk_bf16_f32 v17, v18, v19
	ds_write_b128 v102, v[6:9] offset:17664
	ds_write_b128 v102, v[14:17] offset:17680
	ds_write_b128 v102, v[2:5] offset:26880
	ds_write_b128 v102, v[10:13] offset:26896
	v_add_u32_e32 v12, 0x1c00, v0
	v_add_u32_e32 v10, 0x4000, v0
	ds_read2_b32 v[2:3], v12 offset0:223 offset1:239
	ds_read2_b32 v[4:5], v10 offset0:64 offset1:80
	v_add_u32_e32 v11, 0x1e00, v0
	s_waitcnt lgkmcnt(0)
	v_add_f32_e32 v2, v2, v4
	v_mul_f32_e32 v2, 0x3fb8aa3b, v2
	v_exp_f32_e32 v2, v2
	s_nop 0
	v_mul_f32_e32 v4, v68, v2
	v_cvt_pk_bf16_f32 v4, v4, s0
	ds_write_b16 v120, v4 offset:63744
	v_mul_f32_e32 v4, v69, v2
	v_cvt_pk_bf16_f32 v4, v4, s0
	ds_write_b16 v120, v4 offset:63888
	v_mul_f32_e32 v4, v70, v2
	v_mul_f32_e32 v2, v71, v2
	v_cvt_pk_bf16_f32 v2, v2, s0
	ds_write_b16 v120, v2 offset:64176
	v_add_f32_e32 v2, v3, v5
	v_mul_f32_e32 v2, 0x3fb8aa3b, v2
	v_exp_f32_e32 v2, v2
	v_cvt_pk_bf16_f32 v4, v4, s0
	ds_write_b16 v120, v4 offset:64032
	v_mul_f32_e32 v3, v72, v2
	v_cvt_pk_bf16_f32 v3, v3, s0
	ds_write_b16 v120, v3 offset:63776
	v_mul_f32_e32 v3, v73, v2
	v_cvt_pk_bf16_f32 v3, v3, s0
	ds_write_b16 v120, v3 offset:63920
	v_mul_f32_e32 v3, v74, v2
	v_mul_f32_e32 v2, v75, v2
	v_cvt_pk_bf16_f32 v3, v3, s0
	v_cvt_pk_bf16_f32 v2, v2, s0
	ds_write_b16 v120, v3 offset:64064
	ds_write_b16 v120, v2 offset:64208
	ds_read2_b32 v[2:3], v11 offset0:127 offset1:143
	ds_read2_b32 v[4:5], v10 offset0:96 offset1:112
	s_waitcnt lgkmcnt(0)
	v_add_f32_e32 v2, v2, v4
	v_mul_f32_e32 v2, 0x3fb8aa3b, v2
	v_exp_f32_e32 v2, v2
	s_nop 0
	v_mul_f32_e32 v4, v76, v2
	v_cvt_pk_bf16_f32 v4, v4, s0
	ds_write_b16 v120, v4 offset:63808
	v_mul_f32_e32 v4, v77, v2
	v_cvt_pk_bf16_f32 v4, v4, s0
	ds_write_b16 v120, v4 offset:63952
	v_mul_f32_e32 v4, v78, v2
	v_mul_f32_e32 v2, v79, v2
	v_cvt_pk_bf16_f32 v2, v2, s0
	ds_write_b16 v120, v2 offset:64240
	v_add_f32_e32 v2, v3, v5
	v_mul_f32_e32 v2, 0x3fb8aa3b, v2
	v_exp_f32_e32 v2, v2
	v_cvt_pk_bf16_f32 v4, v4, s0
	ds_write_b16 v120, v4 offset:64096
	v_mul_f32_e32 v3, v80, v2
	v_cvt_pk_bf16_f32 v3, v3, s0
	ds_write_b16 v120, v3 offset:63840
	v_mul_f32_e32 v3, v81, v2
	v_cvt_pk_bf16_f32 v3, v3, s0
	ds_write_b16 v120, v3 offset:63984
	v_mul_f32_e32 v3, v82, v2
	v_mul_f32_e32 v2, v83, v2
	v_cvt_pk_bf16_f32 v3, v3, s0
	v_cvt_pk_bf16_f32 v2, v2, s0
	ds_write_b16 v120, v3 offset:64128
	ds_write_b16 v120, v2 offset:64272
	s_waitcnt lgkmcnt(0)
	s_barrier
; #define MFMA(a, b, c) __builtin_amdgcn_mfma_f32_16x16x32_bf16((a), (b), (c), 0, 0, 0)
; DI u16 f2bf(float x) { return (u16)pack2(x, 0.f); }
; DI void hgrn_unit(const P& p, int l, int unit, char* lds_all) {
;     ...
;     bf16x8 aq[2];
; #pragma unroll
;     for (int ks = 0; ks < 2; ++ks) aq[ks] = *(const bf16x8*)&Qm[(w * 16 + r) * 72 + ks * 32 + g * 8];
;     f32x4 oacc[4];
; #pragma unroll
;     for (int nt = 0; nt < 4; ++nt) {
;       f32x4 a = zero4();
; #pragma unroll
;       for (int ks = 0; ks < 2; ++ks) {
;         const bf16x8 bk = *(const bf16x8*)&Km[(nt * 16 + r) * 72 + ks * 32 + g * 8];
;         a = MFMA(aq[ks], bk, a);
;       }
; #pragma unroll
;       for (int j = 0; j < 4; ++j) {
;         const bool keep = (nt * 16 + r) <= (w * 16 + g * 4 + j);
;         const float v = keep ? a[j] : 0.f;
;         Att[(w * 16 + g * 4 + j) * 72 + nt * 16 + r] = f2bf(v);
;       }
;     }
; #pragma unroll
;     for (int nt = 0; nt < 4; ++nt) {
;       f32x4 a = zero4();
; #pragma unroll
;       for (int ks = 0; ks < 2; ++ks) {
;         const bf16x8 bs = *(const bf16x8*)&St[(nt * 16 + r) * 72 + ks * 32 + g * 8];
;         a = MFMA(aq[ks], bs, a);
;       }
;       oacc[nt] = a;
;     }
;     __syncthreads();
	ds_read_b128 v[2:5], v121 offset:17664
	ds_read_b128 v[6:9], v121 offset:17728
	ds_read_b128 v[14:17], v122 offset:26880
	ds_read_b128 v[18:21], v122 offset:26944
	s_waitcnt lgkmcnt(1)
	v_mfma_f32_16x16x32_bf16 v[14:17], v[2:5], v[14:17], 0
	s_waitcnt lgkmcnt(0)
	v_mfma_f32_16x16x32_bf16 v[14:17], v[6:9], v[18:21], v[14:17]
	s_nop 7
	v_cvt_pk_bf16_f32 v13, v14, s0
	v_cndmask_b32_e64 v13, v13, 0, s[48:49]
	ds_write_b16 v123, v13 offset:54528
	v_cvt_pk_bf16_f32 v13, v15, s0
	v_cndmask_b32_e64 v13, v13, 0, s[50:51]
	ds_write_b16 v123, v13 offset:54672
	v_cvt_pk_bf16_f32 v13, v16, s0
	v_cndmask_b32_e64 v13, v13, 0, s[52:53]
	ds_write_b16 v123, v13 offset:54816
	v_cvt_pk_bf16_f32 v13, v17, s0
	v_cndmask_b32_e64 v13, v13, 0, s[54:55]
	ds_write_b16 v123, v13 offset:54960
	ds_read_b128 v[14:17], v122 offset:29184
	ds_read_b128 v[18:21], v122 offset:29248
	s_waitcnt lgkmcnt(1)
	v_mfma_f32_16x16x32_bf16 v[14:17], v[2:5], v[14:17], 0
	s_waitcnt lgkmcnt(0)
	v_mfma_f32_16x16x32_bf16 v[14:17], v[6:9], v[18:21], v[14:17]
	s_nop 7
	v_cvt_pk_bf16_f32 v13, v14, s0
	v_cndmask_b32_e64 v13, v13, 0, s[56:57]
	ds_write_b16 v123, v13 offset:54560
	v_cvt_pk_bf16_f32 v13, v15, s0
	v_cndmask_b32_e64 v13, v13, 0, s[58:59]
	ds_write_b16 v123, v13 offset:54704
	v_cvt_pk_bf16_f32 v13, v16, s0
	v_cndmask_b32_e64 v13, v13, 0, s[60:61]
	ds_write_b16 v123, v13 offset:54848
	v_cvt_pk_bf16_f32 v13, v17, s0
	v_cndmask_b32_e64 v13, v13, 0, s[62:63]
	ds_write_b16 v123, v13 offset:54992
	ds_read_b128 v[14:17], v122 offset:31488
	ds_read_b128 v[18:21], v122 offset:31552
	s_waitcnt lgkmcnt(1)
	v_mfma_f32_16x16x32_bf16 v[14:17], v[2:5], v[14:17], 0
	s_waitcnt lgkmcnt(0)
	v_mfma_f32_16x16x32_bf16 v[14:17], v[6:9], v[18:21], v[14:17]
	s_nop 7
	v_cvt_pk_bf16_f32 v13, v14, s0
	v_cndmask_b32_e64 v13, v13, 0, s[64:65]
	ds_write_b16 v123, v13 offset:54592
	v_cvt_pk_bf16_f32 v13, v15, s0
	v_cndmask_b32_e64 v13, v13, 0, s[66:67]
	ds_write_b16 v123, v13 offset:54736
	v_cvt_pk_bf16_f32 v13, v16, s0
	v_cndmask_b32_e64 v13, v13, 0, s[68:69]
	ds_write_b16 v123, v13 offset:54880
	v_cvt_pk_bf16_f32 v13, v17, s0
	v_cndmask_b32_e64 v13, v13, 0, s[70:71]
	ds_write_b16 v123, v13 offset:55024
	ds_read_b128 v[14:17], v122 offset:33792
	ds_read_b128 v[18:21], v122 offset:33856
	s_waitcnt lgkmcnt(1)
	v_mfma_f32_16x16x32_bf16 v[14:17], v[2:5], v[14:17], 0
	s_waitcnt lgkmcnt(0)
	v_mfma_f32_16x16x32_bf16 v[14:17], v[6:9], v[18:21], v[14:17]
	s_nop 7
	v_cvt_pk_bf16_f32 v13, v14, s0
	v_cndmask_b32_e64 v13, v13, 0, s[72:73]
	ds_write_b16 v123, v13 offset:54624
	v_cvt_pk_bf16_f32 v13, v15, s0
	v_cndmask_b32_e64 v13, v13, 0, s[74:75]
	ds_write_b16 v123, v13 offset:54768
	v_cvt_pk_bf16_f32 v13, v16, s0
	v_cndmask_b32_e64 v13, v13, 0, s[76:77]
	ds_write_b16 v123, v13 offset:54912
	v_cvt_pk_bf16_f32 v13, v17, s0
	v_cndmask_b32_e64 v13, v13, 0, s[78:79]
	ds_write_b16 v123, v13 offset:55056
	ds_read_b128 v[14:17], v122 offset:63744
	ds_read_b128 v[18:21], v122 offset:63808
	s_waitcnt lgkmcnt(1)
	v_mfma_f32_16x16x32_bf16 v[14:17], v[2:5], v[14:17], 0
	ds_read_b128 v[22:25], v124 offset:63808
	ds_read_b128 v[84:87], v125 offset:63808
	s_waitcnt lgkmcnt(2)
	v_mfma_f32_16x16x32_bf16 v[14:17], v[6:9], v[18:21], v[14:17]
	ds_read_b128 v[18:21], v124 offset:63744
	s_waitcnt lgkmcnt(0)
	v_mfma_f32_16x16x32_bf16 v[18:21], v[2:5], v[18:21], 0
	v_mfma_f32_16x16x32_bf16 v[18:21], v[6:9], v[22:25], v[18:21]
	ds_read_b128 v[22:25], v125 offset:63744
	s_waitcnt lgkmcnt(0)
	v_mfma_f32_16x16x32_bf16 v[22:25], v[2:5], v[22:25], 0
	v_mfma_f32_16x16x32_bf16 v[22:25], v[6:9], v[84:87], v[22:25]
	ds_read_b128 v[84:87], v126 offset:63744
	s_waitcnt lgkmcnt(0)
	v_mfma_f32_16x16x32_bf16 v[2:5], v[2:5], v[84:87], 0
	ds_read_b128 v[84:87], v126 offset:63808
	s_waitcnt lgkmcnt(0)
	s_barrier
; #define MFMA(a, b, c) __builtin_amdgcn_mfma_f32_16x16x32_bf16((a), (b), (c), 0, 0, 0)
; DI void hgrn_unit(const P& p, int l, int unit, char* lds_all) {
;     ...
;     bf16x8 aa[2], av[2];
; #pragma unroll
;     for (int ks = 0; ks < 2; ++ks) {
;       aa[ks] = *(const bf16x8*)&Att[(w * 16 + r) * 72 + ks * 32 + g * 8];
;       av[ks] = *(const bf16x8*)&Vt[(w * 16 + r) * 72 + ks * 32 + g * 8];
;     }
; #pragma unroll
;     for (int nt = 0; nt < 4; ++nt) {
; #pragma unroll
;       for (int ks = 0; ks < 2; ++ks) {
;         const bf16x8 bv = *(const bf16x8*)&Vt[(nt * 16 + r) * 72 + ks * 32 + g * 8];
;         oacc[nt] = MFMA(aa[ks], bv, oacc[nt]);
;       }
; #pragma unroll
;       for (int j = 0; j < 4; ++j) {
;         const int t = w * 16 + g * 4 + j;
;         const int tk = base + (dir ? 63 - t : t);
;         Og[(size_t)tk * 64 + nt * 16 + r] = oacc[nt][j];
;       }
;     }
; #pragma unroll
;     for (int nt = 0; nt < 4; ++nt) {
;       f32x4 u = zero4();
; #pragma unroll
;       for (int ks = 0; ks < 2; ++ks) {
;         const bf16x8 bk = *(const bf16x8*)&KmT[(nt * 16 + r) * 72 + ks * 32 + g * 8];
;         u = MFMA(av[ks], bk, u);
;       }
;       const int k = nt * 16 + r;
;       const float s0 = Seg[k], s1 = Seg[64 + k], s2 = Seg[128 + k], s3 = Seg[192 + k];
;       const float blast = s0 + s1 + s2 + s3;
;       const float rk = Lf[31 * 65 + k] + s0;
;       const float e1 = __expf(blast), e2 = __expf(blast - rk);
; #pragma unroll
;       for (int j = 0; j < 4; ++j) Sacc[nt][j] = e1 * Sacc[nt][j] + e2 * u[j];
;     }
	v_mfma_f32_16x16x32_bf16 v[84:87], v[6:9], v[84:87], v[2:5]
	ds_read_b128 v[88:91], v113 offset:54528
	ds_read_b128 v[6:9], v113 offset:45312
	ds_read_b128 v[92:95], v113 offset:54592
	s_nop 0
	ds_read_b128 v[2:5], v113 offset:45376
	ds_read_b128 v[128:131], v122 offset:45312
	s_waitcnt lgkmcnt(0)
	v_mfma_f32_16x16x32_bf16 v[14:17], v[88:91], v[128:131], v[14:17]
	ds_read_b128 v[128:131], v122 offset:45376
	s_waitcnt lgkmcnt(0)
	v_mfma_f32_16x16x32_bf16 v[14:17], v[92:95], v[128:131], v[14:17]
	s_nop 7
	global_store_dword v[26:27], v14, off sc1 nt
	v_add_u32_e32 v14, v127, v116
	global_store_dword v[96:97], v15, off sc1 nt
	v_ashrrev_i32_e32 v15, 31, v14
	v_lshlrev_b64 v[14:15], 8, v[14:15]
	v_lshl_add_u64 v[128:129], v[50:51], 0, v[14:15]
	v_add_u32_e32 v14, v127, v117
	v_ashrrev_i32_e32 v15, 31, v14
	v_lshlrev_b64 v[14:15], 8, v[14:15]
	v_lshl_add_u64 v[130:131], v[50:51], 0, v[14:15]
	global_store_dword v[128:129], v16, off sc1 nt
	global_store_dword v[130:131], v17, off sc1 nt
	ds_read_b128 v[14:17], v122 offset:47616
	s_waitcnt lgkmcnt(0)
	v_mfma_f32_16x16x32_bf16 v[14:17], v[88:91], v[14:17], v[18:21]
	s_nop 2
	ds_read_b128 v[18:21], v122 offset:47680
	s_waitcnt lgkmcnt(0)
	v_mfma_f32_16x16x32_bf16 v[14:17], v[92:95], v[18:21], v[14:17]
	s_nop 7
	global_store_dword v[26:27], v14, off offset:64 sc1 nt
	global_store_dword v[96:97], v15, off offset:64 sc1 nt
	global_store_dword v[128:129], v16, off offset:64 sc1 nt
	global_store_dword v[130:131], v17, off offset:64 sc1 nt
	ds_read_b128 v[14:17], v122 offset:49920
	ds_read_b128 v[18:21], v122 offset:49984
	s_waitcnt lgkmcnt(1)
	v_mfma_f32_16x16x32_bf16 v[14:17], v[88:91], v[14:17], v[22:25]
	s_waitcnt lgkmcnt(0)
	v_mfma_f32_16x16x32_bf16 v[14:17], v[92:95], v[18:21], v[14:17]
	s_nop 7
	global_store_dword v[26:27], v14, off offset:128 sc1 nt
	global_store_dword v[96:97], v15, off offset:128 sc1 nt
	global_store_dword v[128:129], v16, off offset:128 sc1 nt
	global_store_dword v[130:131], v17, off offset:128 sc1 nt
	ds_read_b128 v[14:17], v122 offset:52224
	ds_read_b128 v[18:21], v122 offset:52288
	s_waitcnt lgkmcnt(1)
	v_mfma_f32_16x16x32_bf16 v[14:17], v[88:91], v[14:17], v[84:87]
	s_nop 2
	v_add_u32_e32 v86, 0x4400, v0
	s_waitcnt lgkmcnt(0)
	v_mfma_f32_16x16x32_bf16 v[14:17], v[92:95], v[18:21], v[14:17]
	s_nop 7
	global_store_dword v[26:27], v14, off offset:192 sc1 nt
	global_store_dword v[96:97], v15, off offset:192 sc1 nt
	global_store_dword v[128:129], v16, off offset:192 sc1 nt
	global_store_dword v[130:131], v17, off offset:192 sc1 nt
	ds_read_b128 v[14:17], v122 offset:36096
	ds_read_b128 v[18:21], v122 offset:36160
	s_waitcnt lgkmcnt(1)
	v_mfma_f32_16x16x32_bf16 v[14:17], v[6:9], v[14:17], 0
	s_waitcnt lgkmcnt(0)
	v_mfma_f32_16x16x32_bf16 v[14:17], v[2:5], v[18:21], v[14:17]
	ds_read2_b32 v[20:21], v10 offset0:64 offset1:80
	ds_read2_b32 v[22:23], v10 offset0:128 offset1:144
	ds_read2_b32 v[24:25], v10 offset0:192 offset1:208
	ds_read2_b32 v[26:27], v86 offset1:16
	ds_read2_b32 v[84:85], v12 offset0:223 offset1:239
	s_waitcnt lgkmcnt(4)
	v_mov_b32_e32 v19, v20
	s_waitcnt lgkmcnt(3)
	v_add_f32_e32 v13, v20, v22
	s_waitcnt lgkmcnt(2)
	v_add_f32_e32 v18, v13, v24
	s_waitcnt lgkmcnt(1)
	v_mov_b32_e32 v12, v26
	s_waitcnt lgkmcnt(0)
	v_mov_b32_e32 v13, v84
	v_pk_add_f32 v[12:13], v[18:19], v[12:13]
	v_mov_b32_e32 v84, v27
	v_mul_f32_e32 v18, 0x3fb8aa3b, v12
	v_sub_f32_e32 v12, v12, v13
	v_mul_f32_e32 v12, 0x3fb8aa3b, v12
	v_exp_f32_e32 v12, v12
	v_exp_f32_e32 v18, v18
	v_pk_mul_f32 v[16:17], v[16:17], v[12:13] op_sel_hi:[1,0]
	v_pk_mul_f32 v[12:13], v[14:15], v[12:13] op_sel_hi:[1,0]
	v_pk_fma_f32 v[70:71], v[70:71], v[18:19], v[16:17] op_sel_hi:[1,0,1]
	v_pk_fma_f32 v[68:69], v[68:69], v[18:19], v[12:13] op_sel_hi:[1,0,1]
	ds_read_b128 v[12:15], v122 offset:38400
	ds_read_b128 v[16:19], v122 offset:38464
	s_waitcnt lgkmcnt(1)
	v_mfma_f32_16x16x32_bf16 v[12:15], v[6:9], v[12:15], 0
	s_waitcnt lgkmcnt(0)
	v_mfma_f32_16x16x32_bf16 v[12:15], v[2:5], v[16:19], v[12:15]
	v_add_f32_e32 v16, v21, v23
	v_add_f32_e32 v20, v16, v25
	v_pk_add_f32 v[16:17], v[20:21], v[84:85]
	s_nop 0
	v_mul_f32_e32 v18, 0x3fb8aa3b, v16
	v_sub_f32_e32 v16, v16, v17
	v_mul_f32_e32 v16, 0x3fb8aa3b, v16
	v_exp_f32_e32 v16, v16
	v_exp_f32_e32 v18, v18
	v_pk_mul_f32 v[14:15], v[14:15], v[16:17] op_sel_hi:[1,0]
	v_pk_mul_f32 v[12:13], v[12:13], v[16:17] op_sel_hi:[1,0]
	v_pk_fma_f32 v[74:75], v[74:75], v[18:19], v[14:15] op_sel_hi:[1,0,1]
	v_pk_fma_f32 v[72:73], v[72:73], v[18:19], v[12:13] op_sel_hi:[1,0,1]
	ds_read_b128 v[12:15], v122 offset:40704
	ds_read_b128 v[16:19], v122 offset:40768
	s_waitcnt lgkmcnt(1)
	v_mfma_f32_16x16x32_bf16 v[12:15], v[6:9], v[12:15], 0
	s_waitcnt lgkmcnt(0)
	v_mfma_f32_16x16x32_bf16 v[12:15], v[2:5], v[16:19], v[12:15]
	ds_read2_b32 v[16:17], v10 offset0:96 offset1:112
	ds_read2_b32 v[18:19], v10 offset0:160 offset1:176
	ds_read2_b32 v[20:21], v10 offset0:224 offset1:240
	ds_read2_b32 v[22:23], v86 offset0:32 offset1:48
	ds_read2_b32 v[24:25], v11 offset0:127 offset1:143
	s_waitcnt lgkmcnt(4)
	v_mov_b32_e32 v11, v16
	s_waitcnt lgkmcnt(3)
	v_add_f32_e32 v10, v16, v18
	s_waitcnt lgkmcnt(2)
	v_add_f32_e32 v10, v10, v20
	s_waitcnt lgkmcnt(1)
	v_mov_b32_e32 v26, v22
	s_waitcnt lgkmcnt(0)
	v_mov_b32_e32 v27, v24
	v_pk_add_f32 v[10:11], v[10:11], v[26:27]
	v_mov_b32_e32 v24, v23
	v_mul_f32_e32 v16, 0x3fb8aa3b, v10
	v_sub_f32_e32 v10, v10, v11
	v_mul_f32_e32 v10, 0x3fb8aa3b, v10
	v_exp_f32_e32 v10, v10
	v_exp_f32_e32 v16, v16
	v_pk_mul_f32 v[14:15], v[14:15], v[10:11] op_sel_hi:[1,0]
	v_pk_mul_f32 v[10:11], v[12:13], v[10:11] op_sel_hi:[1,0]
	v_pk_fma_f32 v[78:79], v[78:79], v[16:17], v[14:15] op_sel_hi:[1,0,1]
	v_pk_fma_f32 v[76:77], v[76:77], v[16:17], v[10:11] op_sel_hi:[1,0,1]
	ds_read_b128 v[10:13], v122 offset:43008
	s_waitcnt lgkmcnt(0)
	v_mfma_f32_16x16x32_bf16 v[6:9], v[6:9], v[10:13], 0
	ds_read_b128 v[10:13], v122 offset:43072
	s_waitcnt lgkmcnt(0)
	s_barrier
	v_mfma_f32_16x16x32_bf16 v[2:5], v[2:5], v[10:13], v[6:9]
	s_nop 3
	v_add_f32_e32 v6, v17, v19
	v_add_f32_e32 v16, v6, v21
	v_pk_add_f32 v[6:7], v[16:17], v[24:25]
	s_nop 0
	v_mul_f32_e32 v8, 0x3fb8aa3b, v6
	v_sub_f32_e32 v6, v6, v7
	v_mul_f32_e32 v6, 0x3fb8aa3b, v6
	v_exp_f32_e32 v6, v6
	v_exp_f32_e32 v8, v8
	v_pk_mul_f32 v[4:5], v[4:5], v[6:7] op_sel_hi:[1,0]
	v_pk_mul_f32 v[2:3], v[2:3], v[6:7] op_sel_hi:[1,0]
	v_pk_fma_f32 v[82:83], v[82:83], v[8:9], v[4:5] op_sel_hi:[1,0,1]
	v_pk_fma_f32 v[80:81], v[80:81], v[8:9], v[2:3] op_sel_hi:[1,0,1]
	s_cbranch_scc1 .LBB0_938
